# layer-1 w_pg/w_pe/p-row prep moved from phase 7 to idle workgroups of phase 9; phase-0 x-row conversion before the transposes on odd workgroups
# baseline (speedup 1.0000x reference)
_Z8yoco_fwd1Pii:
	s_mov_b64 s[12:13], s[0:1]
	v_writelane_b32 v255, 0, 62
	s_load_dwordx2 s[4:5], s[0:1], 0xb0
	s_nop 0
	s_load_dword s0, s[0:1], 0xb8
	v_and_b32_e32 v1, 0x3ff, v0
	v_writelane_b32 v254, s2, 0
	v_readfirstlane_b32 s14, v1
	s_and_b32 s2, s14, 0x3c0
	s_waitcnt lgkmcnt(0)
	v_writelane_b32 v254, s0, 1
	s_add_u32 s0, s12, 0xb8
	v_writelane_b32 v254, s4, 2
	s_addc_u32 s1, s13, 0
	s_cmp_le_i32 s5, s4
	v_writelane_b32 v254, s5, 3
	v_writelane_b32 v254, s2, 4
	s_cbranch_scc1 .LBB0_14
	v_mov_b32_e32 v3, 0
	v_mov_b32_e32 v2, 0
	v_mbcnt_lo_u32_b32 v3, -1, v3
	v_mbcnt_hi_u32_b32 v3, -1, v3
	v_sub_u32_e32 v3, 0, v3
	v_cmp_eq_u32_e32 vcc, s2, v3
	s_and_saveexec_b64 s[2:3], vcc
	v_mov_b32_e32 v3, v2
	ds_write_b64 v2, v[2:3]
	s_or_b64 exec, exec, s[2:3]
	v_readlane_b32 s2, v254, 0
	s_cmp_lg_u32 s2, 0
	s_cbranch_scc1 .LBB0_13
	v_mov_b32_e32 v2, 0
	v_readlane_b32 s2, v254, 4
	v_mbcnt_lo_u32_b32 v2, -1, v2
	v_mbcnt_hi_u32_b32 v2, -1, v2
	v_add_u32_e32 v2, s2, v2
	s_movk_i32 s2, 0xd80
	v_cmp_gt_i32_e32 vcc, s2, v2
	s_and_saveexec_b64 s[2:3], vcc
	s_cbranch_execz .LBB0_12
	s_load_dwordx2 s[4:5], s[12:13], 0xa8
	v_max_i32_e32 v3, 0xb80, v2
	v_sub_u32_e32 v3, v3, v2
	s_movk_i32 s6, 0x1ff
	v_add_u32_e32 v3, 0x1ff, v3
	v_cmp_lt_u32_e32 vcc, s6, v3
	s_mov_b64 s[8:9], -1
	s_and_saveexec_b64 s[6:7], vcc
	s_cbranch_execz .LBB0_9
	v_lshrrev_b32_e32 v3, 9, v3
	v_add_u32_e32 v6, 1, v3
	s_waitcnt lgkmcnt(0)
	s_add_u32 s8, s4, 0x1caa4500
	v_and_b32_e32 v7, 0xfffffe, v6
	v_add_u32_e32 v3, 0x200, v2
	s_addc_u32 s9, s5, 0
	s_mov_b64 s[10:11], 0
	v_mov_b32_e32 v8, 0
	v_mov_b32_e32 v9, v7
	v_mov_b64_e32 v[4:5], v[2:3]

.Lp0_trans:
	v_readlane_b32 s2, v255, 62
	s_cmp_lg_u32 s2, 0
	s_cbranch_scc1 .Lp0_dotrans
	v_readlane_b32 s2, v254, 0
	s_bitcmp1_b32 s2, 0
	s_cbranch_scc0 .Lp0_dotrans
	s_mov_b32 s2, 1
	v_writelane_b32 v255, s2, 62
	s_waitcnt lgkmcnt(0)
	s_branch .LBB0_26
.Lp0_dotrans:
	v_readlane_b32 s2, v254, 15
	v_readlane_b32 s3, v254, 16
	v_mbcnt_lo_u32_b32 v2, -1, v2
	s_load_dwordx2 s[4:5], s[2:3], 0x38
	s_nop 0
	s_load_dwordx2 s[2:3], s[2:3], 0x48
	v_mbcnt_hi_u32_b32 v2, -1, v2
	v_readlane_b32 s6, v254, 7
	v_readlane_b32 s12, v254, 12
	s_waitcnt lgkmcnt(0)
	s_cmp_lg_u64 s[4:5], 0
	v_add_u32_e32 v3, s6, v2
	v_lshlrev_b32_e32 v2, 4, v2
	v_and_b32_e32 v10, 0xf0, v2
	v_and_b32_e32 v2, 48, v2
	v_mul_u32_u24_e32 v4, 0x41, v2
	v_ashrrev_i32_e32 v21, 4, v3
	v_ashrrev_i32_e32 v23, 2, v3
	v_lshlrev_b32_e32 v4, 2, v4
	v_and_b32_e32 v3, -4, v3
	s_movk_i32 s6, 0x104
	v_lshl_add_u64 v[12:13], s[2:3], 0, v[10:11]
	s_cselect_b64 s[2:3], -1, 0
	v_add3_u32 v24, s91, v4, v3
	v_mul_lo_u32 v3, v21, s6
	v_add3_u32 v25, s91, v3, v10
	v_readlane_b32 s6, v254, 10
	v_cndmask_b32_e64 v3, 0, 1, s[2:3]
	v_add_u32_e32 v26, 0x1040, v25
	v_add_u32_e32 v27, 0x2080, v25
	v_add_u32_e32 v28, 0x30c0, v25
	s_lshl_b32 s10, s6, 6
	s_lshl_b32 s11, s12, 6
	v_cmp_ne_u32_e64 s[2:3], 1, v3
	v_lshlrev_b32_e32 v10, 1, v2
	s_mov_b32 s12, s6
	v_readlane_b32 s7, v254, 11
	v_readlane_b32 s13, v254, 13
	s_branch .LBB0_18

.LBB0_26:
	v_readlane_b32 s2, v255, 62
	s_cmp_eq_u32 s2, 2
	s_cbranch_scc1 .Lp0_after40
	v_readlane_b32 s2, v254, 7
	v_mbcnt_lo_u32_b32 v2, -1, v11
	v_mbcnt_hi_u32_b32 v70, -1, v2
	v_add_u32_e32 v71, s2, v70
	v_ashrrev_i32_e32 v2, 6, v71
	v_readlane_b32 s2, v254, 10
	s_movk_i32 s26, 0x4080
	v_readlane_b32 s3, v254, 11
	v_lshl_add_u32 v50, s2, 2, v2
	v_cmp_gt_i32_e32 vcc, s26, v50
	s_and_saveexec_b64 s[10:11], vcc
	s_cbranch_execz .LBB0_40
	v_mbcnt_lo_u32_b32 v5, -1, 0
	v_mbcnt_hi_u32_b32 v5, -1, v5
	v_and_b32_e32 v6, 64, v5
	v_add_u32_e32 v6, 64, v6
	v_xor_b32_e32 v7, 32, v5
	v_cmp_lt_i32_e32 vcc, v7, v6
	v_readlane_b32 s18, v254, 15
	v_readlane_b32 s19, v254, 16
	v_cndmask_b32_e32 v7, v5, v7, vcc
	v_lshlrev_b32_e32 v72, 2, v7
	v_xor_b32_e32 v7, 16, v5
	v_cmp_lt_i32_e32 vcc, v7, v6
	s_load_dword s15, s[18:19], 0xb8
	s_load_dwordx4 s[4:7], s[18:19], 0x0
	v_cndmask_b32_e32 v7, v5, v7, vcc
	v_lshlrev_b32_e32 v73, 2, v7
	v_xor_b32_e32 v7, 8, v5
	v_cmp_lt_i32_e32 vcc, v7, v6
	v_and_b32_e32 v3, 63, v70
	v_mov_b32_e32 v53, 0
	v_cndmask_b32_e32 v7, v5, v7, vcc
	v_lshlrev_b32_e32 v74, 2, v7
	v_xor_b32_e32 v7, 4, v5
	v_cmp_lt_i32_e32 vcc, v7, v6
	v_lshlrev_b32_e32 v52, 3, v3
	s_mov_b64 s[18:19], 0x2600000
	v_cndmask_b32_e32 v7, v5, v7, vcc
	v_lshlrev_b32_e32 v75, 2, v7
	v_xor_b32_e32 v7, 2, v5
	v_cmp_lt_i32_e32 vcc, v7, v6
	s_waitcnt lgkmcnt(0)
	s_add_u32 s12, s8, 0x1c940000
	s_addc_u32 s13, s9, 0
	v_cndmask_b32_e32 v7, v5, v7, vcc
	v_lshlrev_b32_e32 v76, 2, v7
	v_xor_b32_e32 v7, 1, v5
	v_cmp_lt_i32_e32 vcc, v7, v6
	s_lshl_b32 s14, s15, 3
	s_lshl_b32 s16, s15, 5
	v_cndmask_b32_e32 v5, v5, v7, vcc
	v_lshl_add_u64 v[6:7], s[8:9], 0, v[52:53]
	v_lshl_add_u64 v[54:55], v[6:7], 0, s[18:19]
	v_readlane_b32 s18, v254, 14
	s_lshl_b32 s27, s15, 4
	s_mul_i32 s28, s15, 24
	v_readlane_b32 s15, v254, 0
	s_lshl_b32 s18, s18, 2
	s_lshl_b32 s15, s15, 3
	s_add_i32 s18, s18, s14
	s_add_i32 s18, s18, s15
	v_add_u32_e32 v2, s18, v2
	v_lshlrev_b32_e32 v4, 2, v3
	v_cmp_eq_u32_e64 s[2:3], 0, v3
	v_ashrrev_i32_e32 v51, 31, v50
	v_ashrrev_i32_e32 v3, 31, v2
	s_ashr_i32 s17, s16, 31
	v_mov_b64_e32 v[6:7], 0x1c940000
	v_lshlrev_b64 v[58:59], 11, v[2:3]
	v_lshlrev_b64 v[62:63], 11, v[50:51]
	s_sub_i32 s22, 0, s27
	v_lshlrev_b32_e32 v77, 2, v5
	v_lshl_add_u64 v[56:57], v[2:3], 2, v[6:7]
	s_lshl_b64 s[18:19], s[16:17], 2
	v_or_b32_e32 v58, v58, v52
	s_lshl_b64 s[20:21], s[16:17], 11
	v_lshl_add_u64 v[60:61], v[50:51], 2, v[6:7]
	v_or_b32_e32 v62, v62, v52
	s_ashr_i32 s15, s14, 31
	s_ashr_i32 s23, s22, 31
	s_mov_b64 s[24:25], 0
	s_movk_i32 s29, 0x4000
	v_mov_b32_e32 v78, s7
	v_mov_b32_e32 v79, s5
	v_mov_b32_e32 v80, s6
	v_mov_b32_e32 v81, s4
	v_lshlrev_b32_e32 v52, 2, v4
	s_movk_i32 s6, 0x407f
	s_mov_b32 s7, 0x2600000
	s_branch .LBB0_29

.LBB0_40:
	s_or_b64 exec, exec, s[10:11]
	v_readlane_b32 s2, v255, 62
	s_cmp_eq_u32 s2, 1
	s_cbranch_scc0 .Lp0_after40
	s_mov_b32 s2, 2
	v_writelane_b32 v255, s2, 62
	v_mov_b32_e32 v2, 0
	v_mov_b32_e32 v11, 0
	s_branch .Lp0_trans
.Lp0_after40:
	v_readlane_b32 s2, v254, 10
	v_readlane_b32 s3, v254, 11
	s_nop 0
	v_lshl_add_u32 v2, s2, 8, v71
	v_readlane_b32 s2, v254, 15
	v_readlane_b32 s3, v254, 16
	s_load_dword s2, s[2:3], 0xb8
	s_waitcnt lgkmcnt(0)
	s_lshl_b32 s4, s2, 9
	s_movk_i32 s2, 0x4080
	v_cmp_gt_i32_e32 vcc, s2, v2
	s_and_saveexec_b64 s[6:7], vcc
	s_cbranch_execz .LBB0_48
	v_cvt_f32_u32_e32 v3, s4
	v_readlane_b32 s5, v254, 5
	s_and_b32 s5, s5, 0x300
	v_readlane_b32 s10, v254, 7
	v_rcp_iflag_f32_e32 v3, v3
	v_readlane_b32 s3, v254, 0
	s_or_b32 s5, s10, s5
	s_lshl_b32 s3, s3, 9
	s_add_i32 s5, s5, s4
	s_add_i32 s3, s5, s3
	v_mul_f32_e32 v3, 0x4f7ffffe, v3
	v_add_u32_e32 v4, s3, v70
	v_cvt_u32_f32_e32 v3, v3
	v_mov_b32_e32 v6, s3
	v_cmp_gt_i32_e32 vcc, s2, v4
	v_max_i32_e32 v5, 0x4080, v4
	s_mov_b64 s[10:11], -1
	v_addc_co_u32_e64 v4, s[2:3], v6, v70, vcc
	s_sub_i32 s2, 0, s4
	v_sub_u32_e32 v4, v5, v4
	v_mul_lo_u32 v5, s2, v3
	v_mul_hi_u32 v5, v3, v5
	v_add_u32_e32 v3, v3, v5
	v_mul_hi_u32 v3, v4, v3
	v_mul_lo_u32 v5, v3, s4
	v_sub_u32_e32 v4, v4, v5
	v_add_u32_e32 v5, 1, v3
	v_cmp_le_u32_e64 s[2:3], s4, v4
	s_nop 1
	v_cndmask_b32_e64 v3, v3, v5, s[2:3]
	v_subrev_u32_e32 v5, s4, v4
	v_cndmask_b32_e64 v4, v4, v5, s[2:3]
	v_add_u32_e32 v5, 1, v3
	v_cmp_le_u32_e64 s[2:3], s4, v4
	v_mov_b32_e32 v4, v2
	s_nop 0
	v_cndmask_b32_e64 v3, v3, v5, s[2:3]
	v_addc_co_u32_e32 v6, vcc, 1, v3, vcc
	v_cmp_lt_u32_e32 vcc, 1, v6
	s_and_saveexec_b64 s[2:3], vcc
	s_cbranch_execz .LBB0_45
	v_readlane_b32 s12, v254, 15
	v_readlane_b32 s13, v254, 16
	s_load_dword s5, s[12:13], 0xb8
	s_add_u32 s10, s8, 0x1c950200
	s_addc_u32 s11, s9, 0
	v_and_b32_e32 v7, -2, v6
	v_add_u32_e32 v3, s4, v2
	s_waitcnt lgkmcnt(0)
	s_lshl_b32 s5, s5, 10
	s_mov_b32 s14, s5
	s_mov_b64 s[12:13], 0
	v_mov_b32_e32 v8, 0
	v_mov_b32_e32 v9, v7
	v_mov_b64_e32 v[4:5], v[2:3]

.LBB0_1932:
.LBB0_1942:
	v_readlane_b32 s0, v254, 15
	v_readlane_b32 s1, v254, 16
	s_load_dwordx2 s[6:7], s[0:1], 0xb0
	s_waitcnt lgkmcnt(0)
	s_cmp_lt_i32 s7, 8
	s_cbranch_scc1 .LBB0_1996
	v_mov_b32_e32 v1, 0
	s_waitcnt vmcnt(0)
	v_readlane_b32 s0, v254, 4
	v_mbcnt_lo_u32_b32 v1, -1, v1
	v_mbcnt_hi_u32_b32 v1, -1, v1
	v_sub_u32_e32 v1, 0, v1
	v_mov_b32_e32 v0, 0
	v_cmp_eq_u32_e32 vcc, s0, v1
	s_waitcnt vmcnt(63) expcnt(7) lgkmcnt(15)
	s_barrier
	s_and_saveexec_b64 s[2:3], vcc
	s_cbranch_execz .LBB0_1995
	s_mov_b64 s[0:1], src_shared_base
	v_mov_b32_e32 v1, s1
	s_waitcnt vmcnt(0) expcnt(0) lgkmcnt(0)
	s_getreg_b32 s0, hwreg(HW_REG_XCC_ID, 0, 4)
	flat_load_dword v2, v[0:1] sc0 sc1
	s_waitcnt vmcnt(0)
	v_mov_b32_e32 v0, 4
	flat_load_dword v0, v[0:1] sc0 sc1
	s_waitcnt vmcnt(0)
	s_and_b32 s0, s0, 15
	s_waitcnt lgkmcnt(0)
	v_cmp_eq_u32_e32 vcc, 0, v2
	s_and_saveexec_b64 s[4:5], vcc
	s_cbranch_execz .LBB0_1959
	s_add_u32 s6, s48, 0x1caa4700
	s_addc_u32 s7, s49, 0
	s_add_u32 s8, s48, 0x1caa4900
	s_addc_u32 s9, s49, 0
	s_add_u32 s10, s48, 0x1caa4a00
	s_addc_u32 s11, s49, 0
	s_add_u32 s12, s48, 0x1caa4b00
	s_addc_u32 s13, s49, 0
	s_add_u32 s14, s48, 0x1caa4c00
	s_addc_u32 s15, s49, 0
	s_add_u32 s16, s48, 0x1caa4d00
	s_addc_u32 s17, s49, 0
	s_add_u32 s18, s48, 0x1caa4e00
	s_addc_u32 s19, s49, 0
	s_add_u32 s20, s48, 0x1caa4f00
	s_addc_u32 s21, s49, 0
	s_add_u32 s22, s48, 0x1caa5000
	s_addc_u32 s23, s49, 0
	s_add_u32 s24, s48, 0x1caa5100
	s_addc_u32 s25, s49, 0
	s_add_u32 s26, s48, 0x1caa5200
	s_addc_u32 s27, s49, 0
	s_add_u32 s28, s48, 0x1caa5300
	s_addc_u32 s29, s49, 0
	s_add_u32 s30, s48, 0x1caa5400
	s_addc_u32 s31, s49, 0
	s_add_u32 s34, s48, 0x1caa5500
	s_addc_u32 s35, s49, 0
	s_add_u32 s36, s48, 0x1caa5600
	s_addc_u32 s37, s49, 0
	s_add_u32 s38, s48, 0x1caa5700
	s_addc_u32 s39, s49, 0
	s_add_u32 s40, s48, 0x1caa5800
	s_addc_u32 s41, s49, 0
	s_mov_b32 s1, 1
	v_mov_b32_e32 v16, 0
	s_branch .LBB0_1947

.LBB0_2138:
	v_readlane_b32 s33, v254, 10
	s_cmpk_lt_i32 s33, 0x100
	s_cbranch_scc1 .Lp9_noprep
	s_mov_b64 s[50:51], s[0:1]
	v_mov_b32_e32 v40, v3
	s_addk_i32 s33, 0xff00
	s_movk_i32 s79, 0x100
	v_readlane_b32 s0, v254, 15
	v_readlane_b32 s1, v254, 16
	s_load_dwordx2 s[48:49], s[0:1], 0xa8
	v_mov_b32_e32 v1, 0
	s_waitcnt lgkmcnt(0)

.Lq9_1941:
	s_or_b64 exec, exec, s[2:3]
	s_mov_b64 s[0:1], s[50:51]
	v_mov_b32_e32 v3, v40
